# stack16 + w_in GEMM output Z block-permuted (GELU epilogue quads store whole 64-byte lines); phase_b_mix keeps its physical reads and remaps the lane's logical row / channel octet (thread-index bits [
# speedup vs baseline: 1.0265x; 1.0024x over previous
.LBB0_141:
	s_cmp_gt_i32 s6, 10
	s_mov_b64 s[0:1], -1
	s_cbranch_scc0 .LBB0_153
	v_readlane_b32 s0, v251, 63
	v_mov_b32_e32 v78, v150
	v_readlane_b32 s1, v250, 0
	s_andn2_b64 vcc, exec, s[0:1]
	v_readfirstlane_b32 s0, v78
	s_cbranch_vccnz .LBB0_152
	s_movk_i32 s1, 0x80
	s_ashr_i32 s0, s0, 1
	v_cmp_gt_i32_e64 s[4:5], s1, v78
	s_movk_i32 s1, 0x800
	s_andn2_b32 s0, s0, 31
	v_cmp_gt_i32_e64 s[6:7], s1, v78
	s_ashr_i32 s1, s0, 31
	s_lshl_b64 s[2:3], s[0:1], 1
	v_readlane_b32 s12, v251, 9
	v_bfe_u32 v2, v78, 5, 1
	v_readlane_b32 s13, v251, 10
	s_add_u32 s12, s12, s2
	v_lshlrev_b32_e32 v0, 3, v2
	s_addc_u32 s13, s13, s3
	v_and_b32_e32 v79, 31, v78
	v_lshlrev_b32_e32 v6, 2, v78
	v_lshl_add_u64 v[66:67], s[12:13], 0, v[0:1]
	v_readlane_b32 s12, v250, 1
	v_lshlrev_b32_e32 v80, 3, v78
	v_lshrrev_b32_e32 v4, 2, v78
	v_and_b32_e32 v5, 16, v78
	v_and_b32_e32 v6, 12, v6
	v_mul_u32_u24_e32 v7, 0x110, v79
	v_lshlrev_b32_e32 v2, 4, v2
	v_readlane_b32 s13, v250, 2
	s_add_u32 s2, s12, s2
	v_and_b32_e32 v81, 0xf8, v80
	v_ashrrev_i32_e32 v82, 5, v78
	v_and_or_b32 v4, v4, 3, v0
	s_addc_u32 s3, s13, s3
	s_movk_i32 s1, 0x240
	v_add3_u32 v94, v7, v2, 0
	v_or3_b32 v2, s0, v5, v6
	v_lshl_add_u32 v3, v81, 1, 0
	v_mul_u32_u24_e32 v4, 0x240, v4
	v_lshl_add_u64 v[68:69], s[2:3], 0, v[0:1]
	v_lshlrev_b32_e32 v83, 3, v82
	v_mul_lo_u32 v0, v82, s1
	v_lshlrev_b32_e32 v2, 1, v2
	v_readlane_b32 s0, v249, 40
	v_add_u32_e32 v84, 0x80, v83
	v_add_u32_e32 v85, 0x100, v83
	v_add_u32_e32 v86, 0x180, v83
	v_add_u32_e32 v87, 0x200, v83
	v_add_u32_e32 v88, 0x280, v83
	v_add_u32_e32 v89, 0x300, v83
	v_add_u32_e32 v90, 0x380, v83
	v_or_b32_e32 v91, 32, v79
	v_or_b32_e32 v92, 64, v79
	v_or_b32_e32 v93, 0x60, v79
	v_add3_u32 v95, v4, s0, v2
	v_add_u32_e32 v96, v3, v0
	v_mov_b32_e32 v224, v81
	v_mov_b32_e32 v225, v82
	v_and_b32_e32 v226, 3, v78
	v_bfe_u32 v227, v78, 5, 2
	v_and_b32_e32 v232, 0xffffff9c, v78
	v_lshl_or_b32 v232, v226, 5, v232
	v_or_b32_e32 v232, v232, v227
	v_lshlrev_b32_e32 v233, 3, v232
	v_and_b32_e32 v81, 0xf8, v233
	v_ashrrev_i32_e32 v82, 5, v232
	v_lshlrev_b32_e32 v83, 3, v82
	v_add_u32_e32 v84, 0x80, v83
	v_add_u32_e32 v85, 0x100, v83
	v_add_u32_e32 v86, 0x180, v83
	v_add_u32_e32 v87, 0x200, v83
	v_add_u32_e32 v88, 0x280, v83
	v_add_u32_e32 v89, 0x300, v83
	v_add_u32_e32 v90, 0x380, v83
	v_mul_u32_u24_e32 v233, 0x240, v82
	v_lshl_add_u32 v96, v81, 1, v233
	v_and_b32_e32 v142, 63, v78
	v_lshrrev_b32_e32 v143, 2, v142
	v_and_b32_e32 v144, 3, v142
	v_lshlrev_b32_e32 v145, 4, v144
	v_readfirstlane_b32 s54, v78
	v_mov_b32_e32 v147, 0
	s_lshr_b32 s55, s54, 6
	s_lshr_b32 s58, s55, 2
	s_mul_i32 s55, s55, 0x1400
	s_lshl_b32 s58, s58, 11
	s_add_i32 s55, s55, 0x1ac00
	s_add_i32 s55, s55, s58
	v_readlane_b32 s56, v251, 9
	v_readlane_b32 s57, v251, 10
	v_lshlrev_b32_e32 v146, 13, v143
	v_add_u32_e32 v146, v146, v145
	s_add_u32 s56, s56, s54
	s_addc_u32 s57, s57, 0
	v_lshl_add_u64 v[136:137], s[56:57], 0, v[146:147]
	v_readlane_b32 s56, v250, 1
	v_readlane_b32 s57, v250, 2
	v_lshlrev_b32_e32 v146, 12, v143
	v_add_u32_e32 v146, v146, v145
	s_add_u32 s56, s56, s54
	s_addc_u32 s57, s57, 0
	v_lshl_add_u64 v[138:139], s[56:57], 0, v[146:147]
	v_mul_u32_u24_e32 v140, 0x50, v143
	v_add3_u32 v140, v140, v145, s55
	v_and_b32_e32 v149, -4, v143
	v_add_u32_e32 v149, v149, v144
	v_mul_u32_u24_e32 v149, 0x50, v149
	v_and_b32_e32 v148, 3, v143
	v_lshl_add_u32 v149, v148, 4, v149
	v_add_u32_e32 v149, s55, v149
	v_mul_u32_u24_e32 v141, 0x50, v79
	v_bfe_u32 v148, v78, 5, 1
	v_lshl_add_u32 v141, v148, 3, v141
	v_add_u32_e32 v141, s55, v141
	v_readlane_b32 s12, v251, 0
.LBB0_144:
	s_ashr_i32 s2, s12, 3
	s_and_b32 s0, s2, 0xffffffe0
	v_readlane_b32 s1, v250, 9
	s_add_i32 s0, s0, s1
	s_ashr_i32 s0, s0, 3
	v_readlane_b32 s1, v250, 3
	s_add_i32 s3, s0, s1
	v_readlane_b32 s0, v250, 36
	v_readlane_b32 s1, v250, 37
	s_and_b64 s[0:1], s[0:1], exec
	s_cselect_b32 s14, s3, s2
	v_readlane_b32 s0, v250, 36
	v_readlane_b32 s1, v250, 37
	s_and_b64 s[0:1], s[0:1], exec
	v_readlane_b32 s0, v250, 9
	s_cselect_b32 s0, s0, s12
	s_and_b32 s13, s0, 7
	s_lshl_b32 s15, s13, 7
	v_mov_b32_e32 v181, 0
	v_ashrrev_i32_e32 v184, 4, v78
	v_add_u32_e32 v186, s15, v184
	v_ashrrev_i32_e32 v187, 31, v186
	v_lshlrev_b32_e32 v180, 1, v80
	v_lshlrev_b64 v[186:187], 8, v[186:187]
	v_and_b32_e32 v180, 0xf0, v180
	v_lshl_add_u64 v[186:187], s[98:99], 0, v[186:187]
	v_lshl_add_u64 v[186:187], v[186:187], 0, v[180:181]
	global_load_dwordx4 v[160:163], v[186:187], off
	s_movk_i32 s16, 0x110
	v_mul_lo_u32 v184, v184, s16
	v_add3_u32 v176, s23, v184, v180
	v_add_u32_e32 v182, 0x200, v78
	v_add_u32_e32 v183, 0x1000, v80
	v_ashrrev_i32_e32 v184, 4, v182
	v_add_u32_e32 v186, s15, v184
	v_ashrrev_i32_e32 v187, 31, v186
	v_lshlrev_b32_e32 v180, 1, v183
	v_lshlrev_b64 v[186:187], 8, v[186:187]
	v_and_b32_e32 v180, 0xf0, v180
	v_lshl_add_u64 v[186:187], s[98:99], 0, v[186:187]
	v_lshl_add_u64 v[186:187], v[186:187], 0, v[180:181]
	global_load_dwordx4 v[164:167], v[186:187], off
	v_mul_lo_u32 v184, v184, s16
	v_add3_u32 v177, s23, v184, v180
	v_add_u32_e32 v182, 0x400, v78
	v_add_u32_e32 v183, 0x2000, v80
	v_ashrrev_i32_e32 v184, 4, v182
	v_add_u32_e32 v186, s15, v184
	v_ashrrev_i32_e32 v187, 31, v186
	v_lshlrev_b32_e32 v180, 1, v183
	v_lshlrev_b64 v[186:187], 8, v[186:187]
	v_and_b32_e32 v180, 0xf0, v180
	v_lshl_add_u64 v[186:187], s[98:99], 0, v[186:187]
	v_lshl_add_u64 v[186:187], v[186:187], 0, v[180:181]
	global_load_dwordx4 v[168:171], v[186:187], off
	v_mul_lo_u32 v184, v184, s16
	v_add3_u32 v178, s23, v184, v180
	v_add_u32_e32 v182, 0x600, v78
	v_add_u32_e32 v183, 0x3000, v80
	v_ashrrev_i32_e32 v184, 4, v182
	v_add_u32_e32 v186, s15, v184
	v_ashrrev_i32_e32 v187, 31, v186
	v_lshlrev_b32_e32 v180, 1, v183
	v_lshlrev_b64 v[186:187], 8, v[186:187]
	v_and_b32_e32 v180, 0xf0, v180
	v_lshl_add_u64 v[186:187], s[98:99], 0, v[186:187]
	v_lshl_add_u64 v[186:187], v[186:187], 0, v[180:181]
	global_load_dwordx4 v[172:175], v[186:187], off
	v_mul_lo_u32 v184, v184, s16
	v_add3_u32 v179, s23, v184, v180
	s_lshl_b32 s0, s14, 7
	v_add_u32_e32 v126, s0, v225
	s_lshl_b32 s1, s13, 8
	v_ashrrev_i32_e32 v127, 31, v126
	v_or_b32_e32 v130, s1, v81
	v_readlane_b32 s52, v251, 9
	v_readlane_b32 s53, v251, 10
	v_readlane_b32 s60, v249, 21
	v_readlane_b32 s61, v249, 22
	v_readlane_b32 s62, v249, 23
	v_readlane_b32 s63, v249, 24
	v_lshlrev_b64 v[128:129], 13, v[126:127]
	v_lshlrev_b32_e32 v134, 2, v130
	v_or_b32_e32 v135, s1, v224
	v_lshlrev_b32_e32 v132, 1, v135
	v_mov_b32_e32 v133, 0
	v_lshl_add_u64 v[128:129], s[52:53], 0, v[128:129]
	s_mov_b64 s[0:1], 0x1000
	v_lshl_add_u64 v[128:129], v[128:129], 0, v[132:133]
	global_load_dwordx4 v[102:105], v134, s[60:61]
	v_lshl_add_u64 v[128:129], v[128:129], 0, s[0:1]
	global_load_dwordx4 v[106:109], v134, s[62:63]
	s_mov_b64 s[0:1], 0x20000
	global_load_dwordx4 v[110:113], v134, s[60:61] offset:16
	global_load_dwordx4 v[114:117], v134, s[62:63] offset:16
	global_load_dwordx4 v[118:121], v[128:129], off
	v_lshl_add_u64 v[128:129], v[128:129], 0, s[0:1]
	global_load_dwordx4 v[122:125], v[128:129], off
	v_lshl_add_u64 v[128:129], v[128:129], 0, s[0:1]
	global_load_dwordx4 v[200:203], v[128:129], off
	v_lshl_add_u64 v[128:129], v[128:129], 0, s[0:1]
	global_load_dwordx4 v[204:207], v[128:129], off
	v_lshl_add_u64 v[128:129], v[128:129], 0, s[0:1]
	global_load_dwordx4 v[208:211], v[128:129], off
	v_lshl_add_u64 v[128:129], v[128:129], 0, s[0:1]
	global_load_dwordx4 v[212:215], v[128:129], off
	v_lshl_add_u64 v[128:129], v[128:129], 0, s[0:1]
	global_load_dwordx4 v[216:219], v[128:129], off
	v_lshl_add_u64 v[128:129], v[128:129], 0, s[0:1]
	global_load_dwordx4 v[220:223], v[128:129], off
	s_barrier
	s_and_saveexec_b64 s[2:3], s[4:5]
	s_cbranch_execz .LBB0_146
	v_lshl_add_u32 v2, s14, 7, v78
	v_ashrrev_i32_e32 v3, 31, v2
	v_readlane_b32 s0, v251, 59
	v_lshlrev_b64 v[2:3], 6, v[2:3]
	v_readlane_b32 s1, v251, 60
	s_nop 1
	v_lshl_add_u64 v[14:15], s[0:1], 0, v[2:3]
	global_load_dwordx4 v[2:5], v[14:15], off
	global_load_dwordx4 v[6:9], v[14:15], off offset:16
	global_load_dwordx4 v[10:13], v[14:15], off offset:32
	s_nop 0
	global_load_dwordx4 v[14:17], v[14:15], off offset:48
	s_mov_b32 s0, 0x3a000000
	s_waitcnt vmcnt(0)
	v_add_f32_e32 v0, v2, v4
	s_waitcnt vmcnt(2)
	v_add_f32_e32 v2, v6, v8
	s_waitcnt vmcnt(1)
	v_add_f32_e32 v4, v10, v12
	s_waitcnt vmcnt(0)
	v_add_f32_e32 v6, v14, v16
	v_add_f32_e32 v0, v0, v2
	v_add_f32_e32 v2, v4, v6
	v_add_f32_e32 v3, v3, v5
	v_add_f32_e32 v5, v7, v9
	v_add_f32_e32 v7, v11, v13
	v_add_f32_e32 v8, v15, v17
	v_add_f32_e32 v0, v0, v2
	v_add_f32_e32 v3, v3, v5
	v_add_f32_e32 v4, v7, v8
	v_mul_f32_e32 v2, 0x3a000000, v0
	v_add_f32_e32 v3, v3, v4
	v_mul_f32_e32 v0, v2, v2
	v_fma_f32 v0, v3, s0, -v0
	v_max_f32_e32 v0, 0, v0
	v_add_f32_e32 v0, 0x3727c5ac, v0
	v_mul_f32_e32 v3, 0x4f800000, v0
	v_cmp_gt_f32_e32 vcc, s20, v0
	v_add_u32_e32 v4, 0, v80
	v_add_u32_e32 v4, 0x1a800, v4
	v_cndmask_b32_e32 v0, v0, v3, vcc
	v_sqrt_f32_e32 v3, v0
	s_nop 0
	v_add_u32_e32 v5, -1, v3
	v_add_u32_e32 v6, 1, v3
	v_fma_f32 v7, -v5, v3, v0
	v_fma_f32 v8, -v6, v3, v0
	v_cmp_ge_f32_e64 s[0:1], 0, v7
	s_nop 1
	v_cndmask_b32_e64 v3, v3, v5, s[0:1]
	v_cmp_lt_f32_e64 s[0:1], 0, v8
	s_nop 1
	v_cndmask_b32_e64 v3, v3, v6, s[0:1]
	v_mul_f32_e32 v5, 0x37800000, v3
	v_cndmask_b32_e32 v3, v3, v5, vcc
	v_cmp_class_f32_e32 vcc, v0, v156
	s_nop 1
	v_cndmask_b32_e32 v0, v3, v0, vcc
	v_div_scale_f32 v3, s[0:1], v0, v0, 1.0
	v_rcp_f32_e32 v5, v3
	v_div_scale_f32 v6, vcc, 1.0, v0, 1.0
	v_fma_f32 v7, -v3, v5, 1.0
	v_fmac_f32_e32 v5, v7, v5
	v_mul_f32_e32 v7, v6, v5
	v_fma_f32 v8, -v3, v7, v6
	v_fmac_f32_e32 v7, v8, v5
	v_fma_f32 v3, -v3, v7, v6
	v_div_fmas_f32 v3, v3, v5, v7
	v_div_fixup_f32 v3, v3, v0, 1.0
	ds_write_b64 v4, v[2:3]

.LBB0_150:
	v_add_u32_e32 v74, 0xffffdc00, v0
	v_add_u32_e32 v97, s2, v94
	v_add_u32_e32 v75, 0xffffe500, v0
	ds_read_b64_tr_b16 v[70:71], v74
	ds_read_b64_tr_b16 v[72:73], v75
	s_waitcnt lgkmcnt(0)
	v_add_u32_e32 v74, 0x12100, v97
	ds_read_b128 v[74:77], v74
	s_add_i32 s2, s2, 64
	s_waitcnt lgkmcnt(0)
	v_mfma_f32_32x32x16_bf16 v[50:65], v[70:73], v[74:77], v[50:65]
	v_add_u32_e32 v74, 0x14300, v97
	ds_read_b128 v[74:77], v74
	s_cmp_eq_u32 s2, 0
	s_waitcnt lgkmcnt(0)
	v_mfma_f32_32x32x16_bf16 v[34:49], v[70:73], v[74:77], v[34:49]
	v_add_u32_e32 v74, 0x16500, v97
	ds_read_b128 v[74:77], v74
	s_waitcnt lgkmcnt(0)
	v_mfma_f32_32x32x16_bf16 v[18:33], v[70:73], v[74:77], v[18:33]
	v_add_u32_e32 v74, 0x18700, v97
	ds_read_b128 v[74:77], v74
	s_waitcnt lgkmcnt(0)
	v_mfma_f32_32x32x16_bf16 v[2:17], v[70:73], v[74:77], v[2:17]
	v_add_u32_e32 v74, 0x900, v0
	ds_read_b64_tr_b16 v[70:71], v0
	ds_read_b64_tr_b16 v[72:73], v74
	s_waitcnt lgkmcnt(0)
	v_add_u32_e32 v74, 0x12120, v97
	ds_read_b128 v[74:77], v74
	v_add_u32_e32 v0, 0x4800, v0
	s_waitcnt lgkmcnt(0)
	v_mfma_f32_32x32x16_bf16 v[50:65], v[70:73], v[74:77], v[50:65]
	v_add_u32_e32 v74, 0x14320, v97
	ds_read_b128 v[74:77], v74
	s_waitcnt lgkmcnt(0)
	v_mfma_f32_32x32x16_bf16 v[34:49], v[70:73], v[74:77], v[34:49]
	v_add_u32_e32 v74, 0x16520, v97
	ds_read_b128 v[74:77], v74
	s_waitcnt lgkmcnt(0)
	v_mfma_f32_32x32x16_bf16 v[18:33], v[70:73], v[74:77], v[18:33]
	v_add_u32_e32 v74, 0x18720, v97
	ds_read_b128 v[74:77], v74
	s_waitcnt lgkmcnt(0)
	v_mfma_f32_32x32x16_bf16 v[2:17], v[70:73], v[74:77], v[2:17]
	s_cbranch_scc0 .LBB0_150
	s_waitcnt vmcnt(0)
	s_lshl_b32 s80, s1, 1
	s_lshl_b32 s56, s0, 12
	s_add_i32 s56, s56, s80
	s_mov_b32 s57, 0
	s_mov_b64 s[58:59], 0x10000
	v_lshl_add_u64 v[72:73], v[138:139], 0, s[56:57]
	ds_write_b128 v149, v[160:163]
	ds_write_b128 v149, v[164:167] offset:1280
	ds_write_b128 v149, v[168:171] offset:2560
	ds_write_b128 v149, v[172:175] offset:3840
	s_waitcnt lgkmcnt(0)
	ds_read_b64 v[200:201], v141
	ds_read_b64 v[202:203], v141 offset:16
	ds_read_b64 v[204:205], v141 offset:32
	ds_read_b64 v[206:207], v141 offset:48
	ds_read_b64 v[208:209], v141 offset:2560
	ds_read_b64 v[210:211], v141 offset:2576
	ds_read_b64 v[212:213], v141 offset:2592
	ds_read_b64 v[214:215], v141 offset:2608
	v_add_f32_e32 v50, v50, v192
	v_add_f32_e32 v51, v51, v192
	v_add_f32_e32 v52, v52, v192
	v_add_f32_e32 v53, v53, v192
	v_add_f32_e32 v54, v54, v192
	v_add_f32_e32 v55, v55, v192
	v_add_f32_e32 v56, v56, v192
	v_add_f32_e32 v57, v57, v192
	v_add_f32_e32 v58, v58, v192
	v_add_f32_e32 v59, v59, v192
	v_add_f32_e32 v60, v60, v192
	v_add_f32_e32 v61, v61, v192
	v_add_f32_e32 v62, v62, v192
	v_add_f32_e32 v63, v63, v192
	v_add_f32_e32 v64, v64, v192
	v_add_f32_e32 v65, v65, v192
	v_add_f32_e32 v34, v34, v193
	v_add_f32_e32 v35, v35, v193
	v_add_f32_e32 v36, v36, v193
	v_add_f32_e32 v37, v37, v193
	v_add_f32_e32 v38, v38, v193
	v_add_f32_e32 v39, v39, v193
	v_add_f32_e32 v40, v40, v193
	v_add_f32_e32 v41, v41, v193
	v_add_f32_e32 v42, v42, v193
	v_add_f32_e32 v43, v43, v193
	v_add_f32_e32 v44, v44, v193
	v_add_f32_e32 v45, v45, v193
	v_add_f32_e32 v46, v46, v193
	v_add_f32_e32 v47, v47, v193
	v_add_f32_e32 v48, v48, v193
	v_add_f32_e32 v49, v49, v193
	s_waitcnt lgkmcnt(0)
	v_lshlrev_b32_e32 v216, 16, v200
	v_and_b32_e32 v217, 0xffff0000, v200
	v_lshlrev_b32_e32 v218, 16, v201
	v_and_b32_e32 v219, 0xffff0000, v201
	v_mul_f32_e32 v50, v50, v216
	v_mul_f32_e32 v51, v51, v217
	v_mul_f32_e32 v52, v52, v218
	v_mul_f32_e32 v53, v53, v219
	v_cvt_pk_bf16_f32 v200, v50, v51
	v_cvt_pk_bf16_f32 v201, v52, v53
	ds_write_b64 v141, v[200:201]
	v_lshlrev_b32_e32 v216, 16, v202
	v_and_b32_e32 v217, 0xffff0000, v202
	v_lshlrev_b32_e32 v218, 16, v203
	v_and_b32_e32 v219, 0xffff0000, v203
	v_mul_f32_e32 v54, v54, v216
	v_mul_f32_e32 v55, v55, v217
	v_mul_f32_e32 v56, v56, v218
	v_mul_f32_e32 v57, v57, v219
	v_cvt_pk_bf16_f32 v202, v54, v55
	v_cvt_pk_bf16_f32 v203, v56, v57
	ds_write_b64 v141, v[202:203] offset:16
	v_lshlrev_b32_e32 v216, 16, v204
	v_and_b32_e32 v217, 0xffff0000, v204
	v_lshlrev_b32_e32 v218, 16, v205
	v_and_b32_e32 v219, 0xffff0000, v205
	v_mul_f32_e32 v58, v58, v216
	v_mul_f32_e32 v59, v59, v217
	v_mul_f32_e32 v60, v60, v218
	v_mul_f32_e32 v61, v61, v219
	v_cvt_pk_bf16_f32 v204, v58, v59
	v_cvt_pk_bf16_f32 v205, v60, v61
	ds_write_b64 v141, v[204:205] offset:32
	v_lshlrev_b32_e32 v216, 16, v206
	v_and_b32_e32 v217, 0xffff0000, v206
	v_lshlrev_b32_e32 v218, 16, v207
	v_and_b32_e32 v219, 0xffff0000, v207
	v_mul_f32_e32 v62, v62, v216
	v_mul_f32_e32 v63, v63, v217
	v_mul_f32_e32 v64, v64, v218
	v_mul_f32_e32 v65, v65, v219
	v_cvt_pk_bf16_f32 v206, v62, v63
	v_cvt_pk_bf16_f32 v207, v64, v65
	ds_write_b64 v141, v[206:207] offset:48
	v_lshlrev_b32_e32 v216, 16, v208
	v_and_b32_e32 v217, 0xffff0000, v208
	v_lshlrev_b32_e32 v218, 16, v209
	v_and_b32_e32 v219, 0xffff0000, v209
	v_mul_f32_e32 v34, v34, v216
	v_mul_f32_e32 v35, v35, v217
	v_mul_f32_e32 v36, v36, v218
	v_mul_f32_e32 v37, v37, v219
	v_cvt_pk_bf16_f32 v208, v34, v35
	v_cvt_pk_bf16_f32 v209, v36, v37
	ds_write_b64 v141, v[208:209] offset:2560
	v_lshlrev_b32_e32 v216, 16, v210
	v_and_b32_e32 v217, 0xffff0000, v210
	v_lshlrev_b32_e32 v218, 16, v211
	v_and_b32_e32 v219, 0xffff0000, v211
	v_mul_f32_e32 v38, v38, v216
	v_mul_f32_e32 v39, v39, v217
	v_mul_f32_e32 v40, v40, v218
	v_mul_f32_e32 v41, v41, v219
	v_cvt_pk_bf16_f32 v210, v38, v39
	v_cvt_pk_bf16_f32 v211, v40, v41
	ds_write_b64 v141, v[210:211] offset:2576
	v_lshlrev_b32_e32 v216, 16, v212
	v_and_b32_e32 v217, 0xffff0000, v212
	v_lshlrev_b32_e32 v218, 16, v213
	v_and_b32_e32 v219, 0xffff0000, v213
	v_mul_f32_e32 v42, v42, v216
	v_mul_f32_e32 v43, v43, v217
	v_mul_f32_e32 v44, v44, v218
	v_mul_f32_e32 v45, v45, v219
	v_cvt_pk_bf16_f32 v212, v42, v43
	v_cvt_pk_bf16_f32 v213, v44, v45
	ds_write_b64 v141, v[212:213] offset:2592
	v_lshlrev_b32_e32 v216, 16, v214
	v_and_b32_e32 v217, 0xffff0000, v214
	v_lshlrev_b32_e32 v218, 16, v215
	v_and_b32_e32 v219, 0xffff0000, v215
	v_mul_f32_e32 v46, v46, v216
	v_mul_f32_e32 v47, v47, v217
	v_mul_f32_e32 v48, v48, v218
	v_mul_f32_e32 v49, v49, v219
	v_cvt_pk_bf16_f32 v214, v46, v47
	v_cvt_pk_bf16_f32 v215, v48, v49
	ds_write_b64 v141, v[214:215] offset:2608
	s_waitcnt lgkmcnt(0)
	ds_read_b128 v[160:163], v140
	ds_read_b128 v[164:167], v140 offset:1280
	ds_read_b128 v[168:171], v140 offset:2560
	ds_read_b128 v[172:175], v140 offset:3840
	s_waitcnt lgkmcnt(3)
	global_store_dwordx4 v[72:73], v[160:163], off
	v_lshl_add_u64 v[72:73], v[72:73], 0, s[58:59]
	s_waitcnt lgkmcnt(2)
	global_store_dwordx4 v[72:73], v[164:167], off
	v_lshl_add_u64 v[72:73], v[72:73], 0, s[58:59]
	s_waitcnt lgkmcnt(1)
	global_store_dwordx4 v[72:73], v[168:171], off
	v_lshl_add_u64 v[72:73], v[72:73], 0, s[58:59]
	s_waitcnt lgkmcnt(0)
	global_store_dwordx4 v[72:73], v[172:175], off
	v_lshl_add_u64 v[72:73], v[72:73], 0, s[58:59]
	ds_write_b128 v149, v[176:179]
	ds_write_b128 v149, v[180:183] offset:1280
	ds_write_b128 v149, v[184:187] offset:2560
	ds_write_b128 v149, v[188:191] offset:3840
	s_waitcnt lgkmcnt(0)
	ds_read_b64 v[200:201], v141
	ds_read_b64 v[202:203], v141 offset:16
	ds_read_b64 v[204:205], v141 offset:32
	ds_read_b64 v[206:207], v141 offset:48
	ds_read_b64 v[208:209], v141 offset:2560
	ds_read_b64 v[210:211], v141 offset:2576
	ds_read_b64 v[212:213], v141 offset:2592
	ds_read_b64 v[214:215], v141 offset:2608
	v_add_f32_e32 v18, v18, v194
	v_add_f32_e32 v19, v19, v194
	v_add_f32_e32 v20, v20, v194
	v_add_f32_e32 v21, v21, v194
	v_add_f32_e32 v22, v22, v194
	v_add_f32_e32 v23, v23, v194
	v_add_f32_e32 v24, v24, v194
	v_add_f32_e32 v25, v25, v194
	v_add_f32_e32 v26, v26, v194
	v_add_f32_e32 v27, v27, v194
	v_add_f32_e32 v28, v28, v194
	v_add_f32_e32 v29, v29, v194
	v_add_f32_e32 v30, v30, v194
	v_add_f32_e32 v31, v31, v194
	v_add_f32_e32 v32, v32, v194
	v_add_f32_e32 v33, v33, v194
	v_add_f32_e32 v2, v2, v195
	v_add_f32_e32 v3, v3, v195
	v_add_f32_e32 v4, v4, v195
	v_add_f32_e32 v5, v5, v195
	v_add_f32_e32 v6, v6, v195
	v_add_f32_e32 v7, v7, v195
	v_add_f32_e32 v8, v8, v195
	v_add_f32_e32 v9, v9, v195
	v_add_f32_e32 v10, v10, v195
	v_add_f32_e32 v11, v11, v195
	v_add_f32_e32 v12, v12, v195
	v_add_f32_e32 v13, v13, v195
	v_add_f32_e32 v14, v14, v195
	v_add_f32_e32 v15, v15, v195
	v_add_f32_e32 v16, v16, v195
	v_add_f32_e32 v17, v17, v195
	s_waitcnt lgkmcnt(0)
	v_lshlrev_b32_e32 v216, 16, v200
	v_and_b32_e32 v217, 0xffff0000, v200
	v_lshlrev_b32_e32 v218, 16, v201
	v_and_b32_e32 v219, 0xffff0000, v201
	v_mul_f32_e32 v18, v18, v216
	v_mul_f32_e32 v19, v19, v217
	v_mul_f32_e32 v20, v20, v218
	v_mul_f32_e32 v21, v21, v219
	v_cvt_pk_bf16_f32 v200, v18, v19
	v_cvt_pk_bf16_f32 v201, v20, v21
	ds_write_b64 v141, v[200:201]
	v_lshlrev_b32_e32 v216, 16, v202
	v_and_b32_e32 v217, 0xffff0000, v202
	v_lshlrev_b32_e32 v218, 16, v203
	v_and_b32_e32 v219, 0xffff0000, v203
	v_mul_f32_e32 v22, v22, v216
	v_mul_f32_e32 v23, v23, v217
	v_mul_f32_e32 v24, v24, v218
	v_mul_f32_e32 v25, v25, v219
	v_cvt_pk_bf16_f32 v202, v22, v23
	v_cvt_pk_bf16_f32 v203, v24, v25
	ds_write_b64 v141, v[202:203] offset:16
	v_lshlrev_b32_e32 v216, 16, v204
	v_and_b32_e32 v217, 0xffff0000, v204
	v_lshlrev_b32_e32 v218, 16, v205
	v_and_b32_e32 v219, 0xffff0000, v205
	v_mul_f32_e32 v26, v26, v216
	v_mul_f32_e32 v27, v27, v217
	v_mul_f32_e32 v28, v28, v218
	v_mul_f32_e32 v29, v29, v219
	v_cvt_pk_bf16_f32 v204, v26, v27
	v_cvt_pk_bf16_f32 v205, v28, v29
	ds_write_b64 v141, v[204:205] offset:32
	v_lshlrev_b32_e32 v216, 16, v206
	v_and_b32_e32 v217, 0xffff0000, v206
	v_lshlrev_b32_e32 v218, 16, v207
	v_and_b32_e32 v219, 0xffff0000, v207
	v_mul_f32_e32 v30, v30, v216
	v_mul_f32_e32 v31, v31, v217
	v_mul_f32_e32 v32, v32, v218
	v_mul_f32_e32 v33, v33, v219
	v_cvt_pk_bf16_f32 v206, v30, v31
	v_cvt_pk_bf16_f32 v207, v32, v33
	ds_write_b64 v141, v[206:207] offset:48
	v_lshlrev_b32_e32 v216, 16, v208
	v_and_b32_e32 v217, 0xffff0000, v208
	v_lshlrev_b32_e32 v218, 16, v209
	v_and_b32_e32 v219, 0xffff0000, v209
	v_mul_f32_e32 v2, v2, v216
	v_mul_f32_e32 v3, v3, v217
	v_mul_f32_e32 v4, v4, v218
	v_mul_f32_e32 v5, v5, v219
	v_cvt_pk_bf16_f32 v208, v2, v3
	v_cvt_pk_bf16_f32 v209, v4, v5
	ds_write_b64 v141, v[208:209] offset:2560
	v_lshlrev_b32_e32 v216, 16, v210
	v_and_b32_e32 v217, 0xffff0000, v210
	v_lshlrev_b32_e32 v218, 16, v211
	v_and_b32_e32 v219, 0xffff0000, v211
	v_mul_f32_e32 v6, v6, v216
	v_mul_f32_e32 v7, v7, v217
	v_mul_f32_e32 v8, v8, v218
	v_mul_f32_e32 v9, v9, v219
	v_cvt_pk_bf16_f32 v210, v6, v7
	v_cvt_pk_bf16_f32 v211, v8, v9
	ds_write_b64 v141, v[210:211] offset:2576
	v_lshlrev_b32_e32 v216, 16, v212
	v_and_b32_e32 v217, 0xffff0000, v212
	v_lshlrev_b32_e32 v218, 16, v213
	v_and_b32_e32 v219, 0xffff0000, v213
	v_mul_f32_e32 v10, v10, v216
	v_mul_f32_e32 v11, v11, v217
	v_mul_f32_e32 v12, v12, v218
	v_mul_f32_e32 v13, v13, v219
	v_cvt_pk_bf16_f32 v212, v10, v11
	v_cvt_pk_bf16_f32 v213, v12, v13
	ds_write_b64 v141, v[212:213] offset:2592
	v_lshlrev_b32_e32 v216, 16, v214
	v_and_b32_e32 v217, 0xffff0000, v214
	v_lshlrev_b32_e32 v218, 16, v215
	v_and_b32_e32 v219, 0xffff0000, v215
	v_mul_f32_e32 v14, v14, v216
	v_mul_f32_e32 v15, v15, v217
	v_mul_f32_e32 v16, v16, v218
	v_mul_f32_e32 v17, v17, v219
	v_cvt_pk_bf16_f32 v214, v14, v15
	v_cvt_pk_bf16_f32 v215, v16, v17
	ds_write_b64 v141, v[214:215] offset:2608
	s_waitcnt lgkmcnt(0)
	ds_read_b128 v[176:179], v140
	ds_read_b128 v[180:183], v140 offset:1280
	ds_read_b128 v[184:187], v140 offset:2560
	ds_read_b128 v[188:191], v140 offset:3840
	s_waitcnt lgkmcnt(3)
	global_store_dwordx4 v[72:73], v[176:179], off
	v_lshl_add_u64 v[72:73], v[72:73], 0, s[58:59]
	s_waitcnt lgkmcnt(2)
	global_store_dwordx4 v[72:73], v[180:183], off
	v_lshl_add_u64 v[72:73], v[72:73], 0, s[58:59]
	s_waitcnt lgkmcnt(1)
	global_store_dwordx4 v[72:73], v[184:187], off
	v_lshl_add_u64 v[72:73], v[72:73], 0, s[58:59]
	s_waitcnt lgkmcnt(0)
	global_store_dwordx4 v[72:73], v[188:191], off
	v_readlane_b32 s52, v249, 13
	v_readlane_b32 s53, v249, 14
	v_readlane_b32 s54, v249, 15
	v_readlane_b32 s55, v249, 16
	v_readlane_b32 s56, v249, 17
	v_readlane_b32 s57, v249, 18
	v_readlane_b32 s58, v249, 19
	v_readlane_b32 s59, v249, 20
	v_readlane_b32 s62, v249, 23
	v_readlane_b32 s63, v249, 24
	v_readlane_b32 s64, v249, 25
	v_readlane_b32 s65, v249, 26
	v_readlane_b32 s66, v249, 27
	v_readlane_b32 s67, v249, 28
	v_readlane_b32 s23, v249, 41
	v_readlane_b32 s60, v248, 31
	v_readlane_b32 s61, v248, 32
	s_add_i32 s12, s12, s34
	s_cmpk_gt_i32 s12, 0x3ff
	s_cbranch_scc0 .LBB0_144

.LBB0_363:
	ds_read_b128 v[144:147], v173
	v_mov_b64_e32 v[184:185], s[90:91]
	s_lshl_b32 s65, s18, 8
	v_and_b32_e32 v236, 15, v150
	v_bfe_u32 v237, v150, 4, 2
	v_lshrrev_b32_e32 v238, 2, v236
	v_lshl_or_b32 v237, v238, 2, v237
	v_and_b32_e32 v236, 3, v236
	v_lshlrev_b32_e32 v236, 3, v236
	v_and_or_b32 v238, v159, -16, v237
	v_lshrrev_b32_e32 v239, 5, v161
	v_lshl_or_b32 v239, v239, 5, v236
	v_add_u32_e32 v140, s65, v238
	v_ashrrev_i32_e32 v141, 31, v140
	s_waitcnt lgkmcnt(0)
	v_mov_b32_e32 v180, v145
	v_mov_b32_e32 v181, v146
	v_mov_b32_e32 v145, v147
	v_pk_add_f32 v[144:145], v[180:181], v[144:145]
	v_mul_lo_u32 v182, s68, v141
	v_add_f32_e32 v144, v144, v145
	v_fmamk_f32 v144, v144, 0x3a800000, v155
	v_rsq_f32_e32 v146, v144
	v_mul_lo_u32 v183, s69, v140
	v_mad_u64_u32 v[148:149], s[10:11], s68, v140, 0
	v_pk_mul_f32 v[180:181], v[124:125], v[146:147] op_sel_hi:[1,0]
	v_pk_mul_f32 v[118:119], v[118:119], v[146:147] op_sel_hi:[1,0]
	v_and_b32_e32 v195, 0x7fffffff, v181
	v_and_b32_e32 v194, 0x7fffffff, v180
	v_pk_fma_f32 v[194:195], v[194:195], s[72:73], 1.0 op_sel_hi:[1,0,0]
	v_pk_mul_f32 v[128:129], v[128:129], v[146:147] op_sel_hi:[1,0]
	v_rcp_f32_e32 v194, v194
	v_rcp_f32_e32 v195, v195
	v_add3_u32 v149, v149, v182, v183
	v_pk_mul_f32 v[126:127], v[126:127], v[146:147] op_sel_hi:[1,0]
	v_and_b32_e32 v187, 0x7fffffff, v129
	v_pk_fma_f32 v[196:197], v[194:195], s[86:87], v[184:185] op_sel_hi:[1,0,0]
	v_and_b32_e32 v186, 0x7fffffff, v128
	v_pk_fma_f32 v[196:197], v[194:195], v[196:197], s[22:23] op_sel_hi:[1,1,0]
	v_lshl_add_u64 v[144:145], v[148:149], 1, s[78:79]
	v_pk_fma_f32 v[196:197], v[194:195], v[196:197], s[24:25] op_sel_hi:[1,1,0]
	v_and_b32_e32 v149, 0x7fffffff, v127
	v_pk_fma_f32 v[196:197], v[194:195], v[196:197], s[26:27] op_sel_hi:[1,1,0]
	v_and_b32_e32 v148, 0x7fffffff, v126
	v_pk_mul_f32 v[194:195], v[194:195], v[196:197]
	v_and_b32_e32 v197, 0x7fffffff, v119
	v_and_b32_e32 v196, 0x7fffffff, v118
	v_pk_fma_f32 v[196:197], v[196:197], s[72:73], 1.0 op_sel_hi:[1,0,0]
	v_pk_fma_f32 v[186:187], v[186:187], s[72:73], 1.0 op_sel_hi:[1,0,0]
	v_rcp_f32_e32 v196, v196
	v_rcp_f32_e32 v197, v197
	v_pk_fma_f32 v[148:149], v[148:149], s[72:73], 1.0 op_sel_hi:[1,0,0]
	v_rcp_f32_e32 v186, v186
	v_rcp_f32_e32 v187, v187
	v_rcp_f32_e32 v148, v148
	v_rcp_f32_e32 v149, v149
	v_pk_mul_f32 v[200:201], v[114:115], v[146:147] op_sel_hi:[1,0]
	v_pk_fma_f32 v[114:115], v[196:197], s[86:87], v[184:185] op_sel_hi:[1,0,0]
	v_pk_mul_f32 v[182:183], v[122:123], v[146:147] op_sel_hi:[1,0]
	v_pk_fma_f32 v[114:115], v[196:197], v[114:115], s[22:23] op_sel_hi:[1,1,0]
	v_pk_fma_f32 v[188:189], v[186:187], s[86:87], v[184:185] op_sel_hi:[1,0,0]
	v_pk_fma_f32 v[114:115], v[196:197], v[114:115], s[24:25] op_sel_hi:[1,1,0]
	v_pk_mul_f32 v[120:121], v[120:121], v[146:147] op_sel_hi:[1,0]
	v_pk_mul_f32 v[198:199], v[116:117], v[146:147] op_sel_hi:[1,0]
	v_pk_fma_f32 v[114:115], v[196:197], v[114:115], s[26:27] op_sel_hi:[1,1,0]
	v_pk_mul_f32 v[146:147], v[118:119], v[118:119]
	v_pk_fma_f32 v[122:123], v[148:149], s[86:87], v[184:185] op_sel_hi:[1,0,0]
	v_pk_fma_f32 v[188:189], v[186:187], v[188:189], s[22:23] op_sel_hi:[1,1,0]
	v_pk_mul_f32 v[114:115], v[196:197], v[114:115]
	v_pk_mul_f32 v[146:147], v[146:147], s[28:29] op_sel_hi:[1,0]
	v_and_b32_e32 v197, 0x7fffffff, v121
	v_and_b32_e32 v196, 0x7fffffff, v120
	v_pk_fma_f32 v[122:123], v[148:149], v[122:123], s[22:23] op_sel_hi:[1,1,0]
	v_pk_fma_f32 v[188:189], v[186:187], v[188:189], s[24:25] op_sel_hi:[1,1,0]
	v_exp_f32_e32 v146, v146
	v_exp_f32_e32 v147, v147
	v_pk_fma_f32 v[196:197], v[196:197], s[72:73], 1.0 op_sel_hi:[1,0,0]
	v_pk_fma_f32 v[122:123], v[148:149], v[122:123], s[24:25] op_sel_hi:[1,1,0]
	v_pk_fma_f32 v[188:189], v[186:187], v[188:189], s[26:27] op_sel_hi:[1,1,0]
	v_rcp_f32_e32 v196, v196
	v_rcp_f32_e32 v197, v197
	v_pk_fma_f32 v[122:123], v[148:149], v[122:123], s[26:27] op_sel_hi:[1,1,0]
	v_pk_mul_f32 v[186:187], v[186:187], v[188:189]
	v_and_b32_e32 v189, 0x7fffffff, v183
	v_and_b32_e32 v188, 0x7fffffff, v182
	v_pk_mul_f32 v[122:123], v[148:149], v[122:123]
	v_pk_mul_f32 v[148:149], v[126:127], v[126:127]
	v_pk_fma_f32 v[188:189], v[188:189], s[72:73], 1.0 op_sel_hi:[1,0,0]
	v_pk_mul_f32 v[148:149], v[148:149], s[28:29] op_sel_hi:[1,0]
	v_rcp_f32_e32 v188, v188
	v_rcp_f32_e32 v189, v189
	v_pk_mul_f32 v[116:117], v[120:121], v[120:121]
	v_pk_mul_f32 v[114:115], v[146:147], v[114:115]
	v_exp_f32_e32 v148, v148
	v_exp_f32_e32 v149, v149
	v_pk_mul_f32 v[146:147], v[118:119], v[114:115]
	v_pk_fma_f32 v[202:203], v[118:119], v[114:115], v[118:119] neg_lo:[1,0,0] neg_hi:[1,0,0]
	v_pk_fma_f32 v[114:115], v[196:197], s[86:87], v[184:185] op_sel_hi:[1,0,0]
	v_pk_mul_f32 v[116:117], v[116:117], s[28:29] op_sel_hi:[1,0]
	v_pk_mul_f32 v[124:125], v[128:129], v[128:129]
	v_pk_fma_f32 v[114:115], v[196:197], v[114:115], s[22:23] op_sel_hi:[1,1,0]
	v_exp_f32_e32 v116, v116
	v_exp_f32_e32 v117, v117
	v_pk_mul_f32 v[124:125], v[124:125], s[28:29] op_sel_hi:[1,0]
	v_pk_fma_f32 v[114:115], v[196:197], v[114:115], s[24:25] op_sel_hi:[1,1,0]
	v_exp_f32_e32 v124, v124
	v_exp_f32_e32 v125, v125
	v_pk_fma_f32 v[190:191], v[188:189], s[86:87], v[184:185] op_sel_hi:[1,0,0]
	v_pk_fma_f32 v[114:115], v[196:197], v[114:115], s[26:27] op_sel_hi:[1,1,0]
	v_pk_mul_f32 v[122:123], v[148:149], v[122:123]
	v_pk_fma_f32 v[190:191], v[188:189], v[190:191], s[22:23] op_sel_hi:[1,1,0]
	v_pk_mul_f32 v[192:193], v[182:183], v[182:183]
	v_pk_mul_f32 v[114:115], v[196:197], v[114:115]
	v_pk_mul_f32 v[148:149], v[126:127], v[122:123]
	v_pk_fma_f32 v[122:123], v[126:127], v[122:123], v[126:127] neg_lo:[1,0,0] neg_hi:[1,0,0]
	v_pk_fma_f32 v[190:191], v[188:189], v[190:191], s[24:25] op_sel_hi:[1,1,0]
	v_pk_mul_f32 v[192:193], v[192:193], s[28:29] op_sel_hi:[1,0]
	v_pk_mul_f32 v[114:115], v[116:117], v[114:115]
	v_cmp_gt_f32_e32 vcc, 0, v126
	v_pk_fma_f32 v[190:191], v[188:189], v[190:191], s[26:27] op_sel_hi:[1,1,0]
	v_exp_f32_e32 v192, v192
	v_exp_f32_e32 v193, v193
	v_pk_mul_f32 v[196:197], v[120:121], v[114:115]
	v_pk_fma_f32 v[204:205], v[120:121], v[114:115], v[120:121] neg_lo:[1,0,0] neg_hi:[1,0,0]
	v_cndmask_b32_e32 v114, v122, v148, vcc
	v_cmp_gt_f32_e32 vcc, 0, v118
	v_pk_mul_f32 v[124:125], v[124:125], v[186:187]
	v_pk_mul_f32 v[188:189], v[188:189], v[190:191]
	v_pk_mul_f32 v[190:191], v[180:181], v[180:181]
	v_cndmask_b32_e32 v115, v202, v146, vcc
	v_cmp_gt_f32_e32 vcc, 0, v127
	v_pk_mul_f32 v[186:187], v[128:129], v[124:125]
	v_pk_fma_f32 v[124:125], v[128:129], v[124:125], v[128:129] neg_lo:[1,0,0] neg_hi:[1,0,0]
	v_pk_mul_f32 v[190:191], v[190:191], s[28:29] op_sel_hi:[1,0]
	v_cndmask_b32_e32 v122, v123, v149, vcc
	v_cmp_gt_f32_e32 vcc, 0, v128
	v_exp_f32_e32 v190, v190
	v_exp_f32_e32 v191, v191
	v_cndmask_b32_e32 v116, v124, v186, vcc
	v_cmp_gt_f32_e32 vcc, 0, v119
	v_pk_mul_f32 v[188:189], v[192:193], v[188:189]
	v_and_b32_e32 v128, 0x7fffffff, v200
	v_cndmask_b32_e32 v117, v203, v147, vcc
	v_cmp_gt_f32_e32 vcc, 0, v129
	v_pk_mul_f32 v[192:193], v[182:183], v[188:189]
	v_pk_fma_f32 v[188:189], v[182:183], v[188:189], v[182:183] neg_lo:[1,0,0] neg_hi:[1,0,0]
	v_cndmask_b32_e32 v124, v125, v187, vcc
	v_cmp_gt_f32_e32 vcc, 0, v182
	v_and_b32_e32 v129, 0x7fffffff, v201
	v_pk_fma_f32 v[128:129], v[128:129], s[72:73], 1.0 op_sel_hi:[1,0,0]
	v_cndmask_b32_e32 v118, v188, v192, vcc
	v_cmp_gt_f32_e32 vcc, 0, v120
	v_pk_mul_f32 v[190:191], v[190:191], v[194:195]
	v_rcp_f32_e32 v182, v128
	v_cndmask_b32_e32 v119, v204, v196, vcc
	v_cmp_gt_f32_e32 vcc, 0, v183
	v_rcp_f32_e32 v183, v129
	v_lshl_or_b32 v142, s80, 8, v239
	v_pk_mul_f32 v[194:195], v[180:181], v[190:191]
	v_pk_fma_f32 v[190:191], v[180:181], v[190:191], v[180:181] neg_lo:[1,0,0] neg_hi:[1,0,0]
	v_cndmask_b32_e32 v126, v189, v193, vcc
	v_cmp_gt_f32_e32 vcc, 0, v180
	v_ashrrev_i32_e32 v143, 31, v142
	v_lshl_add_u64 v[144:145], v[142:143], 1, v[144:145]
	v_cndmask_b32_e32 v120, v190, v194, vcc
	v_cmp_gt_f32_e32 vcc, 0, v121
	v_cvt_pk_bf16_f32 v146, v114, v122
	v_cvt_pk_bf16_f32 v147, v116, v124
	v_cvt_pk_bf16_f32 v148, v118, v126
	s_cmp_gt_i32 s80, 7
	s_cselect_b64 s[2:3], -1, 0
	v_cndmask_b32_e32 v121, v205, v197, vcc
	v_cmp_gt_f32_e32 vcc, 0, v181
	v_pk_mul_f32 v[180:181], v[200:201], v[200:201]
	s_cmp_lt_i32 s80, 8
	v_cndmask_b32_e32 v128, v191, v195, vcc
	v_cvt_pk_bf16_f32 v149, v120, v128
	global_store_dwordx4 v[144:145], v[146:149], off
	v_pk_mul_f32 v[180:181], v[180:181], s[28:29] op_sel_hi:[1,0]
	v_cmp_gt_f32_e32 vcc, 0, v198
	v_pk_fma_f32 v[146:147], v[182:183], s[86:87], v[184:185] op_sel_hi:[1,0,0]
	v_exp_f32_e32 v180, v180
	v_pk_fma_f32 v[146:147], v[182:183], v[146:147], s[22:23] op_sel_hi:[1,1,0]
	v_exp_f32_e32 v181, v181
	v_pk_fma_f32 v[146:147], v[182:183], v[146:147], s[24:25] op_sel_hi:[1,1,0]
	v_pk_mul_f32 v[148:149], v[198:199], v[198:199]
	v_pk_fma_f32 v[146:147], v[182:183], v[146:147], s[26:27] op_sel_hi:[1,1,0]
	v_pk_mul_f32 v[148:149], v[148:149], s[28:29] op_sel_hi:[1,0]
	v_pk_mul_f32 v[146:147], v[182:183], v[146:147]
	v_and_b32_e32 v183, 0x7fffffff, v199
	v_and_b32_e32 v182, 0x7fffffff, v198
	v_pk_fma_f32 v[182:183], v[182:183], s[72:73], 1.0 op_sel_hi:[1,0,0]
	v_pk_mul_f32 v[146:147], v[180:181], v[146:147]
	v_rcp_f32_e32 v182, v182
	v_rcp_f32_e32 v183, v183
	v_pk_mul_f32 v[180:181], v[200:201], v[146:147]
	v_pk_fma_f32 v[186:187], v[200:201], v[146:147], v[200:201] neg_lo:[1,0,0] neg_hi:[1,0,0]
	v_exp_f32_e32 v148, v148
	v_pk_fma_f32 v[146:147], v[182:183], s[86:87], v[184:185] op_sel_hi:[1,0,0]
	v_exp_f32_e32 v149, v149
	v_pk_fma_f32 v[146:147], v[182:183], v[146:147], s[22:23] op_sel_hi:[1,1,0]
	s_nop 0
	v_pk_fma_f32 v[146:147], v[182:183], v[146:147], s[24:25] op_sel_hi:[1,1,0]
	s_nop 0
	v_pk_fma_f32 v[146:147], v[182:183], v[146:147], s[26:27] op_sel_hi:[1,1,0]
	s_nop 0
	v_pk_mul_f32 v[146:147], v[182:183], v[146:147]
	s_nop 0
	v_pk_mul_f32 v[146:147], v[148:149], v[146:147]
	s_nop 0
	v_pk_mul_f32 v[148:149], v[198:199], v[146:147]
	v_pk_fma_f32 v[182:183], v[198:199], v[146:147], v[198:199] neg_lo:[1,0,0] neg_hi:[1,0,0]
	s_nop 0
	v_cndmask_b32_e32 v147, v182, v148, vcc
	v_cmp_gt_f32_e32 vcc, 0, v200
	s_nop 1
	v_cndmask_b32_e32 v146, v186, v180, vcc
	v_cmp_gt_f32_e32 vcc, 0, v199
	v_cvt_pk_bf16_f32 v180, v115, v117
	s_nop 1
	v_cndmask_b32_e32 v149, v183, v149, vcc
	v_cmp_gt_f32_e32 vcc, 0, v201
	s_nop 1
	v_cndmask_b32_e32 v148, v187, v181, vcc
	v_cvt_pk_bf16_f32 v181, v119, v121
	v_cvt_pk_bf16_f32 v182, v146, v148
	v_cvt_pk_bf16_f32 v183, v147, v149
	global_store_dwordx4 v[144:145], v[180:183], off offset:256
	s_cbranch_scc1 .LBB0_367
	v_mov_b32_e32 v123, v115
	v_mov_b32_e32 v125, v117
	v_pk_mul_f32 v[180:181], v[122:123], v[122:123]
	v_pk_add_f32 v[194:195], v[114:115], v[122:123]
	v_pk_mul_f32 v[122:123], v[114:115], v[122:123]
	v_mov_b32_e32 v127, v119
	v_pk_mul_f32 v[184:185], v[124:125], v[124:125]
	v_mov_b32_e32 v195, v123
	v_pk_add_f32 v[122:123], v[116:117], v[124:125]
	v_pk_mul_f32 v[124:125], v[116:117], v[124:125]
	v_mov_b32_e32 v129, v121
	v_pk_mul_f32 v[188:189], v[126:127], v[126:127]
	v_mov_b32_e32 v123, v125
	v_pk_add_f32 v[124:125], v[118:119], v[126:127]
	v_pk_mul_f32 v[126:127], v[118:119], v[126:127]
	v_pk_mul_f32 v[144:145], v[114:115], v[114:115]
	v_pk_mul_f32 v[192:193], v[128:129], v[128:129]
	v_mov_b32_e32 v125, v127
	v_pk_add_f32 v[126:127], v[120:121], v[128:129]
	v_pk_mul_f32 v[128:129], v[120:121], v[128:129]
	v_pk_mul_f32 v[182:183], v[116:117], v[116:117]
	v_mov_b32_e32 v127, v129
	v_pk_mul_f32 v[128:129], v[148:149], v[148:149]
	v_pk_mov_b32 v[114:115], v[114:115], v[144:145] op_sel:[1,0]
	v_pk_mov_b32 v[116:117], v[116:117], v[180:181] op_sel:[1,0]
	v_pk_mul_f32 v[186:187], v[118:119], v[118:119]
	v_pk_fma_f32 v[128:129], v[146:147], v[146:147], v[128:129]
	v_pk_add_f32 v[114:115], v[114:115], v[116:117]
	v_pk_mov_b32 v[116:117], v[118:119], v[182:183] op_sel:[1,0]
	v_pk_mov_b32 v[118:119], v[120:121], v[184:185] op_sel:[1,0]
	v_pk_add_f32 v[128:129], v[128:129], v[128:129] op_sel_hi:[0,1]
	v_and_b32_e32 v187, 64, v158
	v_pk_add_f32 v[116:117], v[116:117], v[118:119]
	v_pk_mul_f32 v[190:191], v[120:121], v[120:121]
	v_xor_b32_e32 v128, 16, v158
	v_add_u32_e32 v187, 64, v187
	v_pk_add_f32 v[114:115], v[114:115], v[116:117]
	v_mov_b32_e32 v116, v146
	v_mov_b32_e32 v117, v186
	v_mov_b32_e32 v118, v148
	v_mov_b32_e32 v119, v188
	v_cmp_lt_i32_e32 vcc, v128, v187
	v_pk_add_f32 v[116:117], v[116:117], v[118:119]
	v_pk_mov_b32 v[118:119], v[146:147], v[190:191] op_sel:[1,0]
	v_pk_mov_b32 v[120:121], v[148:149], v[192:193] op_sel:[1,0]
	v_cndmask_b32_e32 v128, v158, v128, vcc
	v_pk_add_f32 v[122:123], v[194:195], v[122:123]
	v_pk_add_f32 v[124:125], v[124:125], v[126:127]
	v_pk_add_f32 v[118:119], v[118:119], v[120:121]
	v_lshlrev_b32_e32 v189, 2, v128
	v_pk_add_f32 v[122:123], v[122:123], v[124:125]
	v_mov_b32_e32 v128, v1
	v_pk_add_f32 v[116:117], v[116:117], v[118:119]
	v_pk_add_f32 v[122:123], v[122:123], v[128:129]
	v_pk_add_f32 v[114:115], v[114:115], v[116:117]
	v_xor_b32_e32 v118, 32, v158
	v_pk_add_f32 v[114:115], v[114:115], v[122:123]
	ds_bpermute_b32 v116, v189, v114
	ds_bpermute_b32 v117, v189, v115
	v_cmp_lt_i32_e32 vcc, v118, v187
	s_waitcnt lgkmcnt(0)
	v_pk_add_f32 v[114:115], v[114:115], v[116:117]
	v_cndmask_b32_e32 v118, v158, v118, vcc
	v_lshlrev_b32_e32 v118, 2, v118
	ds_bpermute_b32 v116, v118, v114
	ds_bpermute_b32 v117, v118, v115
	s_and_saveexec_b64 s[10:11], s[4:5]
	s_cbranch_execz .LBB0_366
	s_waitcnt lgkmcnt(0)
	v_pk_add_f32 v[114:115], v[114:115], v[116:117]
	v_add_u32_e32 v116, s60, v170
	ds_write_b64 v116, v[114:115]

.LBB0_394:
	s_or_b64 exec, exec, s[2:3]
	s_waitcnt lgkmcnt(0)
	s_barrier
	s_mov_b64 s[2:3], exec
	v_readlane_b32 s10, v248, 24
	v_readlane_b32 s11, v248, 25
	s_and_b64 s[10:11], s[2:3], s[10:11]
	s_mov_b64 exec, s[10:11]
	s_cbranch_execz .LBB0_396
	s_waitcnt lgkmcnt(0)
	ds_read_b128 v[2:5], v170
	ds_read_b128 v[6:9], v170 offset:16
	v_readlane_b32 s18, v251, 59
	v_add_u32_e32 v240, s65, v159
	v_ashrrev_i32_e32 v241, 31, v240
	v_lshlrev_b64 v[10:11], 6, v[240:241]
	v_readlane_b32 s19, v251, 60
	s_lshl_b64 s[10:11], s[80:81], 3
	s_waitcnt lgkmcnt(0)
	v_pk_add_f32 v[2:3], v[2:3], v[4:5]
	v_lshl_add_u64 v[10:11], s[18:19], 0, v[10:11]
	v_pk_add_f32 v[4:5], v[6:7], v[8:9]
	v_lshl_add_u64 v[10:11], v[10:11], 0, s[10:11]
	v_pk_add_f32 v[2:3], v[2:3], v[4:5]
	global_store_dwordx2 v[10:11], v[2:3], off offset:-64
	ds_read_b128 v[2:5], v174
	ds_read_b128 v[6:9], v174 offset:16
	v_add_u32_e32 v10, s65, v164
	v_ashrrev_i32_e32 v11, 31, v10
	v_lshlrev_b64 v[10:11], 6, v[10:11]
	v_lshl_add_u64 v[10:11], s[18:19], 0, v[10:11]
	s_waitcnt lgkmcnt(0)
	v_pk_add_f32 v[2:3], v[2:3], v[4:5]
	v_pk_add_f32 v[4:5], v[6:7], v[8:9]
	v_lshl_add_u64 v[10:11], v[10:11], 0, s[10:11]
	v_pk_add_f32 v[2:3], v[2:3], v[4:5]
	global_store_dwordx2 v[10:11], v[2:3], off offset:-64
	ds_read_b128 v[2:5], v175
	ds_read_b128 v[6:9], v175 offset:16
	v_add_u32_e32 v10, s65, v165
	v_ashrrev_i32_e32 v11, 31, v10
	v_lshlrev_b64 v[10:11], 6, v[10:11]
	v_lshl_add_u64 v[10:11], s[18:19], 0, v[10:11]
	s_waitcnt lgkmcnt(0)
	v_pk_add_f32 v[2:3], v[2:3], v[4:5]
	v_pk_add_f32 v[4:5], v[6:7], v[8:9]
	v_lshl_add_u64 v[10:11], v[10:11], 0, s[10:11]
	v_pk_add_f32 v[2:3], v[2:3], v[4:5]
	global_store_dwordx2 v[10:11], v[2:3], off offset:-64
	ds_read_b128 v[2:5], v176
	ds_read_b128 v[6:9], v176 offset:16
	v_add_u32_e32 v10, s65, v166
	v_ashrrev_i32_e32 v11, 31, v10
	v_lshlrev_b64 v[10:11], 6, v[10:11]
	v_lshl_add_u64 v[10:11], s[18:19], 0, v[10:11]
	s_waitcnt lgkmcnt(0)
	v_pk_add_f32 v[2:3], v[2:3], v[4:5]
	v_pk_add_f32 v[4:5], v[6:7], v[8:9]
	v_lshl_add_u64 v[10:11], v[10:11], 0, s[10:11]
	v_pk_add_f32 v[2:3], v[2:3], v[4:5]
	global_store_dwordx2 v[10:11], v[2:3], off offset:-64
	ds_read_b128 v[2:5], v171
	ds_read_b128 v[6:9], v171 offset:16
	v_add_u32_e32 v10, s65, v163
	v_ashrrev_i32_e32 v11, 31, v10
	v_lshlrev_b64 v[10:11], 6, v[10:11]
	v_lshl_add_u64 v[10:11], s[18:19], 0, v[10:11]
	s_waitcnt lgkmcnt(0)
	v_pk_add_f32 v[2:3], v[2:3], v[4:5]
	v_pk_add_f32 v[4:5], v[6:7], v[8:9]
	v_lshl_add_u64 v[10:11], v[10:11], 0, s[10:11]
	v_pk_add_f32 v[2:3], v[2:3], v[4:5]
	global_store_dwordx2 v[10:11], v[2:3], off offset:-64
	ds_read_b128 v[2:5], v177
	ds_read_b128 v[6:9], v177 offset:16
	v_add_u32_e32 v10, s65, v167
	v_ashrrev_i32_e32 v11, 31, v10
	v_lshlrev_b64 v[10:11], 6, v[10:11]
	v_lshl_add_u64 v[10:11], s[18:19], 0, v[10:11]
	s_waitcnt lgkmcnt(0)
	v_pk_add_f32 v[2:3], v[2:3], v[4:5]
	v_pk_add_f32 v[4:5], v[6:7], v[8:9]
	v_lshl_add_u64 v[10:11], v[10:11], 0, s[10:11]
	v_pk_add_f32 v[2:3], v[2:3], v[4:5]
	global_store_dwordx2 v[10:11], v[2:3], off offset:-64
	ds_read_b128 v[2:5], v178
	ds_read_b128 v[6:9], v178 offset:16
	v_add_u32_e32 v10, s65, v168
	v_ashrrev_i32_e32 v11, 31, v10
	v_lshlrev_b64 v[10:11], 6, v[10:11]
	v_lshl_add_u64 v[10:11], s[18:19], 0, v[10:11]
	s_waitcnt lgkmcnt(0)
	v_pk_add_f32 v[2:3], v[2:3], v[4:5]
	v_pk_add_f32 v[4:5], v[6:7], v[8:9]
	v_lshl_add_u64 v[10:11], v[10:11], 0, s[10:11]
	v_pk_add_f32 v[2:3], v[2:3], v[4:5]
	global_store_dwordx2 v[10:11], v[2:3], off offset:-64
	ds_read_b128 v[2:5], v179
	ds_read_b128 v[6:9], v179 offset:16
	v_add_u32_e32 v10, s65, v169
	v_ashrrev_i32_e32 v11, 31, v10
	v_lshlrev_b64 v[10:11], 6, v[10:11]
	v_lshl_add_u64 v[10:11], s[18:19], 0, v[10:11]
	s_waitcnt lgkmcnt(0)
	v_pk_add_f32 v[2:3], v[2:3], v[4:5]
	v_pk_add_f32 v[4:5], v[6:7], v[8:9]
	v_lshl_add_u64 v[10:11], v[10:11], 0, s[10:11]
	v_pk_add_f32 v[2:3], v[2:3], v[4:5]
	global_store_dwordx2 v[10:11], v[2:3], off offset:-64
